# layer-0 input norm pass: 64-lane sum of squares via 4 DPP adds + 4 v_readlane instead of 6 serialized LDS lane shuffles per row
# baseline (speedup 1.0000x reference)
; __device__ __forceinline__ float wave_sum(float v) {
; #pragma unroll
;     for (int o = 1; o < 64; o <<= 1) v += __shfl_xor(v, o);
;     return v;
; }
; __device__ __forceinline__ void xpass(const float* x, bf16_t* xb, float* rs, int gw, int NGW, int lane) {
;     for (int m = gw; m < MT; m += NGW) {
;         const f32x4* xr = (const f32x4*)(x + (size_t)m * DM) + lane;
;         f32x4 v[4]; float s = 0.f;
; #pragma unroll
;         for (int j = 0; j < 4; ++j) { v[j] = xr[64 * j]; s += (v[j].x * v[j].x + v[j].y * v[j].y) + (v[j].z * v[j].z + v[j].w * v[j].w); }
;         s = wave_sum(s);
;         if (lane < 16) rs[(size_t)m * 16 + lane] = (lane == 0) ? s : 0.f;
.LBB0_527:
	global_load_dwordx4 v[14:17], v[20:21], off offset:-3072
	global_load_dwordx4 v[2:5], v[20:21], off offset:-2048
	global_load_dwordx4 v[6:9], v[20:21], off offset:-1024
	global_load_dwordx4 v[10:13], v[20:21], off
	s_waitcnt vmcnt(0)
	v_mul_f32_e32 v0, v15, v15
	s_waitcnt lgkmcnt(0)
	v_mul_f32_e32 v30, v17, v17
	v_mul_f32_e32 v31, v3, v3
	v_mul_f32_e32 v32, v5, v5
	v_mul_f32_e32 v33, v7, v7
	v_mul_f32_e32 v34, v9, v9
	v_fmac_f32_e32 v0, v14, v14
	v_fmac_f32_e32 v30, v16, v16
	v_fmac_f32_e32 v31, v2, v2
	v_fmac_f32_e32 v32, v4, v4
	v_mul_f32_e32 v35, v11, v11
	v_mul_f32_e32 v36, v13, v13
	v_fmac_f32_e32 v33, v6, v6
	v_fmac_f32_e32 v34, v8, v8
	v_add_f32_e32 v0, v0, v30
	v_add_f32_e32 v30, v31, v32
	v_fmac_f32_e32 v35, v10, v10
	v_fmac_f32_e32 v36, v12, v12
	v_add_f32_e32 v31, v33, v34
	v_add_f32_e32 v0, v0, v30
	v_add_f32_e32 v0, v0, v31
	v_add_f32_e32 v30, v35, v36
	v_add_f32_e32 v0, v0, v30
	s_nop 1
	v_add_f32_dpp v0, v0, v0 quad_perm:[1,0,3,2] row_mask:0xf bank_mask:0xf
	s_nop 1
	v_add_f32_dpp v0, v0, v0 quad_perm:[2,3,0,1] row_mask:0xf bank_mask:0xf
	s_nop 1
	v_add_f32_dpp v0, v0, v0 row_half_mirror row_mask:0xf bank_mask:0xf
	s_nop 1
	v_add_f32_dpp v0, v0, v0 row_mirror row_mask:0xf bank_mask:0xf
	s_nop 0
	v_readlane_b32 s95, v0, 0
	v_readlane_b32 s96, v0, 16
	v_readlane_b32 s97, v0, 32
	v_readlane_b32 s6, v0, 48
	s_nop 1
	v_mov_b32_e32 v0, s95
	v_mov_b32_e32 v30, s97
	v_add_f32_e32 v0, s96, v0
	v_add_f32_e32 v30, s6, v30
	s_nop 0
	v_add_f32_e32 v0, v0, v30
	s_and_saveexec_b64 s[6:7], vcc
	s_cbranch_execz .LBB0_526
	v_cndmask_b32_e64 v0, 0, v0, s[4:5]
	global_store_dword v[18:19], v0, off
	s_branch .LBB0_526
